# code placement inside the attention steady loop: first and last part of the body moved by +4 bytes (4-byte pads), middle unchanged
# baseline (speedup 1.0000x reference)
; #define WAIT_BAR(N) asm volatile("s_waitcnt vmcnt(" #N ") lgkmcnt(0)\n\ts_barrier" ::: "memory")
; #define RESC() do { if (!FIXM && resc) { asm volatile("s_waitcnt lgkmcnt(0)" ::: "memory"); \
;       _Pragma("unroll") for (int d_ = 0; d_ < 2; ++d_) _Pragma("unroll") for (int r = 0; r < 16; ++r) o[d_][r] *= wsf[crow(r, hi)]; } } while (0)
; #define ROT() do { sl_prev = sl_cur; sl_cur = sl_next; sl_next = (sl_next == (NSLOT - 1) * SLOTB) ? 0 : sl_next + SLOTB; } while (0)
; template <int THRL, bool FIXM> __device__ __forceinline__ bool attn_unit(const h16* Qrows, const h16* __restrict__ Kh, const h16* __restrict__ Vh, const int NT, h16* Yrows, const h16* BZrows, char* shm, const int tid, const float mfix, ...
;     ...
;   int t = 1;
;   for (; t + 5 < NT; t += 2) {
;     STEP(pB0, pB1, pA0, pA1, t, true, true, true);     WAIT_BAR(2); RESC(); ROT();
.LBB0_77:
	s_nop 0
	v_add_u32_e32 v0, s44, v233
	ds_read_b64_tr_b16 v[62:63], v0 offset:24576
	ds_read_b64_tr_b16 v[64:65], v0 offset:25088
	v_add_f32_e32 v51, v82, v83
	v_add_f32_e32 v51, v84, v51
	v_add_f32_e32 v51, v85, v51
	v_add_f32_e32 v51, v86, v51
	v_add_f32_e32 v51, v87, v51
	v_cvt_pk_f16_f32 v160, v82, v83
	v_cvt_pk_f16_f32 v161, v84, v85
	s_waitcnt lgkmcnt(9)
	v_mfma_f32_32x32x16_f16 v[114:129], v[192:195], v[144:147], v[2:17]
	ds_read_b64_tr_b16 v[82:83], v0 offset:28672
	ds_read_b64_tr_b16 v[84:85], v0 offset:29184
	v_add_f32_e32 v51, v88, v51
	v_add_f32_e32 v51, v89, v51
	v_add_f32_e32 v51, v90, v51
	v_add_f32_e32 v51, v91, v51
	v_cvt_pk_f16_f32 v162, v86, v87
	v_cvt_pk_f16_f32 v163, v88, v89
	s_waitcnt lgkmcnt(10)
	v_mfma_f32_32x32x16_f16 v[98:113], v[188:191], v[144:147], v[2:17]
	ds_read_b64_tr_b16 v[86:87], v0 offset:25600
	ds_read_b64_tr_b16 v[88:89], v0 offset:26112
	v_add_f32_e32 v51, v92, v51
	v_add_f32_e32 v51, v93, v51
	v_add_f32_e32 v51, v94, v51
	v_add_f32_e32 v51, v95, v51
	v_cvt_pk_f16_f32 v156, v90, v91
	v_cvt_pk_f16_f32 v157, v92, v93
	s_waitcnt lgkmcnt(11)
	v_mfma_f32_32x32x16_f16 v[114:129], v[184:187], v[140:143], v[114:129]
	ds_read_b64_tr_b16 v[90:91], v0 offset:29696
	ds_read_b64_tr_b16 v[92:93], v0 offset:30208
	v_add_f32_e32 v51, v96, v51
	v_add_f32_e32 v51, v97, v51
	v_add_f32_e32 v51, v66, v51
	v_add_f32_e32 v51, v67, v51
	v_cvt_pk_f16_f32 v158, v94, v95
	v_cvt_pk_f16_f32 v159, v96, v97
	s_waitcnt lgkmcnt(12)
	v_mfma_f32_32x32x16_f16 v[98:113], v[180:183], v[140:143], v[98:113]
	ds_read_b64_tr_b16 v[94:95], v0 offset:26624
	ds_read_b64_tr_b16 v[96:97], v0 offset:27136
	v_add_f32_e32 v51, v68, v51
	v_add_f32_e32 v51, v69, v51
	v_add_f32_e32 v51, v70, v51
	v_add_f32_e32 v51, v71, v51
	v_cvt_pk_f16_f32 v152, v66, v67
	v_cvt_pk_f16_f32 v153, v68, v69
	s_waitcnt lgkmcnt(13)
	v_mfma_f32_32x32x16_f16 v[114:129], v[176:179], v[136:139], v[114:129]
	ds_read_b64_tr_b16 v[66:67], v0 offset:30720
	ds_read_b64_tr_b16 v[68:69], v0 offset:31232
	v_add_f32_e32 v51, v72, v51
	v_add_f32_e32 v51, v73, v51
	v_add_f32_e32 v51, v74, v51
	v_add_f32_e32 v51, v75, v51
	v_cvt_pk_f16_f32 v154, v70, v71
	v_cvt_pk_f16_f32 v155, v72, v73
	s_waitcnt lgkmcnt(14)
	v_mfma_f32_32x32x16_f16 v[98:113], v[172:175], v[136:139], v[98:113]
	ds_read_b64_tr_b16 v[70:71], v0 offset:27648
	ds_read_b64_tr_b16 v[72:73], v0 offset:28160
	v_add_f32_e32 v51, v76, v51
	v_add_f32_e32 v51, v77, v51
	v_add_f32_e32 v51, v78, v51
	v_add_f32_e32 v51, v79, v51
	v_cvt_pk_f16_f32 v148, v74, v75
	v_cvt_pk_f16_f32 v149, v76, v77
	s_waitcnt lgkmcnt(14)
	v_mfma_f32_32x32x16_f16 v[114:129], v[168:171], v[132:135], v[114:129]
	ds_read_b64_tr_b16 v[74:75], v0 offset:31744
	ds_read_b64_tr_b16 v[76:77], v0 offset:32256
	v_add_f32_e32 v0, v80, v51
	v_add_f32_e32 v0, v81, v0
	s_nop 0
	v_add_f32_e32 v0, 0, v0
	v_cvt_pk_f16_f32 v150, v78, v79
	v_cvt_pk_f16_f32 v151, v80, v81
	v_mfma_f32_32x32x16_f16 v[98:113], v[164:167], v[132:135], v[98:113]
	v_add_f32_e32 v0, v50, v0
	s_add_i32 s43, s42, s97
	s_mov_b32 s44, m0
	s_mov_b32 m0, s43
	s_nop 0
	global_load_lds_dwordx4 v214, s[100:101]
	s_mov_b32 m0, s44
	s_add_i32 s43, s25, s83
	s_mov_b32 s44, m0
	s_mov_b32 m0, s43
	s_nop 0
	global_load_lds_dwordx4 v208, vcc
	s_mov_b32 m0, s44
	s_add_u32 s100, s100, 0x2000
	s_addc_u32 s101, s101, 0
	s_add_u32 vcc_lo, vcc_lo, 0x2000
	s_addc_u32 vcc_hi, vcc_hi, 0
	s_waitcnt lgkmcnt(14)
	v_mfma_f32_32x32x16_f16 v[18:33], v[160:163], v[62:65], v[18:33]
	v_exp_f32_e32 v114, v114
	v_exp_f32_e32 v115, v115
	v_exp_f32_e32 v116, v116
	v_exp_f32_e32 v117, v117
	s_waitcnt lgkmcnt(12)
	v_mfma_f32_32x32x16_f16 v[34:49], v[160:163], v[82:85], v[34:49]
	v_exp_f32_e32 v118, v118
	v_exp_f32_e32 v119, v119
	v_exp_f32_e32 v120, v120
	v_exp_f32_e32 v121, v121
	v_add_u32_e32 v50, s25, v219
	ds_read_b128 v[62:65], v50
	ds_read_b128 v[164:167], v50 offset:512
	s_waitcnt lgkmcnt(12)
	v_mfma_f32_32x32x16_f16 v[18:33], v[156:159], v[86:89], v[18:33]
	v_exp_f32_e32 v122, v122
	v_exp_f32_e32 v123, v123
	v_exp_f32_e32 v124, v124
	v_exp_f32_e32 v125, v125
	ds_read_b128 v[168:171], v50 offset:2048
	ds_read_b128 v[172:175], v50 offset:2560
	s_waitcnt lgkmcnt(12)
	v_mfma_f32_32x32x16_f16 v[34:49], v[156:159], v[90:93], v[34:49]
	v_exp_f32_e32 v126, v126
	v_exp_f32_e32 v127, v127
	v_exp_f32_e32 v128, v128
	v_exp_f32_e32 v129, v129
	ds_read_b128 v[176:179], v50 offset:4096
	ds_read_b128 v[180:183], v50 offset:4608
	s_waitcnt lgkmcnt(12)
	v_mfma_f32_32x32x16_f16 v[18:33], v[152:155], v[94:97], v[18:33]
	v_exp_f32_e32 v98, v98
	v_exp_f32_e32 v99, v99
	v_exp_f32_e32 v100, v100
	v_exp_f32_e32 v101, v101
	ds_read_b128 v[184:187], v50 offset:6144
	ds_read_b128 v[50:53], v50 offset:6656
	s_waitcnt lgkmcnt(12)
	v_mfma_f32_32x32x16_f16 v[34:49], v[152:155], v[66:69], v[34:49]
	v_exp_f32_e32 v102, v102
	v_exp_f32_e32 v103, v103
	v_exp_f32_e32 v104, v104
	v_exp_f32_e32 v105, v105
	s_waitcnt lgkmcnt(10)
	v_mfma_f32_32x32x16_f16 v[18:33], v[148:151], v[70:73], v[18:33]
	v_exp_f32_e32 v106, v106
	v_exp_f32_e32 v107, v107
	v_exp_f32_e32 v108, v108
	v_exp_f32_e32 v109, v109
	s_waitcnt lgkmcnt(8)
	v_mfma_f32_32x32x16_f16 v[34:49], v[148:151], v[74:77], v[34:49]
	v_exp_f32_e32 v110, v110
	v_exp_f32_e32 v111, v111
	v_exp_f32_e32 v112, v112
	v_exp_f32_e32 v113, v113
	s_waitcnt vmcnt(2) lgkmcnt(8)
	s_barrier
; #define WAIT_BAR(N) asm volatile("s_waitcnt vmcnt(" #N ") lgkmcnt(0)\n\ts_barrier" ::: "memory")
; #define RESC() do { if (!FIXM && resc) { asm volatile("s_waitcnt lgkmcnt(0)" ::: "memory"); \
;       _Pragma("unroll") for (int d_ = 0; d_ < 2; ++d_) _Pragma("unroll") for (int r = 0; r < 16; ++r) o[d_][r] *= wsf[crow(r, hi)]; } } while (0)
; #define ROT() do { sl_prev = sl_cur; sl_cur = sl_next; sl_next = (sl_next == (NSLOT - 1) * SLOTB) ? 0 : sl_next + SLOTB; } while (0)
; template <int THRL, bool FIXM> __device__ __forceinline__ bool attn_unit(const h16* Qrows, const h16* __restrict__ Kh, const h16* __restrict__ Vh, const int NT, h16* Yrows, const h16* BZrows, char* shm, const int tid, const float mfix, ...
;     ...
;   int t = 1;
;   for (; t + 5 < NT; t += 2) {
;     STEP(pB0, pB1, pA0, pA1, t, true, true, true);     WAIT_BAR(2); RESC(); ROT();
;     STEP(pA0, pA1, pB0, pB1, t + 1, true, true, true); WAIT_BAR(2); RESC(); ROT();
	s_add_i32 s43, s25, 0x2000
	s_cmpk_lg_i32 s25, 0x4000
	s_cselect_b32 s43, s43, 0
	v_add_u32_e32 v192, s42, v233
	ds_read_b64_tr_b16 v[188:189], v192 offset:24576
	ds_read_b64_tr_b16 v[190:191], v192 offset:25088
	s_waitcnt lgkmcnt(9)
	v_mfma_f32_32x32x16_f16 v[82:97], v[62:65], v[144:147], v[2:17]
	v_add_f32_e32 v66, v114, v115
	v_add_f32_e32 v66, v116, v66
	v_add_f32_e32 v66, v117, v66
	v_add_f32_e32 v66, v118, v66
	v_add_f32_e32 v66, v119, v66
	v_cvt_pk_f16_f32 v160, v114, v115
	v_cvt_pk_f16_f32 v161, v116, v117
	ds_read_b64_tr_b16 v[62:63], v192 offset:28672
	ds_read_b64_tr_b16 v[64:65], v192 offset:29184
	v_add_f32_e32 v66, v120, v66
	v_add_f32_e32 v66, v121, v66
	v_add_f32_e32 v66, v122, v66
	v_add_f32_e32 v148, v123, v66
	s_waitcnt lgkmcnt(10)
	v_mfma_f32_32x32x16_f16 v[66:81], v[164:167], v[144:147], v[2:17]
	v_cvt_pk_f16_f32 v162, v118, v119
	v_cvt_pk_f16_f32 v163, v120, v121
	ds_read_b64_tr_b16 v[114:115], v192 offset:25600
	ds_read_b64_tr_b16 v[116:117], v192 offset:26112
	s_waitcnt lgkmcnt(11)
	v_mfma_f32_32x32x16_f16 v[82:97], v[168:171], v[140:143], v[82:97]
	v_add_f32_e32 v118, v124, v148
	v_add_f32_e32 v118, v125, v118
	v_add_f32_e32 v118, v126, v118
	v_add_f32_e32 v148, v127, v118
	v_cvt_pk_f16_f32 v156, v122, v123
	v_cvt_pk_f16_f32 v157, v124, v125
	ds_read_b64_tr_b16 v[118:119], v192 offset:29696
	ds_read_b64_tr_b16 v[120:121], v192 offset:30208
	s_waitcnt lgkmcnt(12)
	v_mfma_f32_32x32x16_f16 v[66:81], v[172:175], v[140:143], v[66:81]
	v_add_f32_e32 v122, v128, v148
	v_add_f32_e32 v122, v129, v122
	v_add_f32_e32 v122, v98, v122
	v_add_f32_e32 v148, v99, v122
	v_cvt_pk_f16_f32 v158, v126, v127
	v_cvt_pk_f16_f32 v159, v128, v129
	ds_read_b64_tr_b16 v[122:123], v192 offset:26624
	ds_read_b64_tr_b16 v[124:125], v192 offset:27136
	s_waitcnt lgkmcnt(13)
	v_mfma_f32_32x32x16_f16 v[82:97], v[176:179], v[136:139], v[82:97]
	v_add_f32_e32 v126, v100, v148
	v_add_f32_e32 v126, v101, v126
	v_add_f32_e32 v126, v102, v126
	v_add_f32_e32 v126, v103, v126
	v_cvt_pk_f16_f32 v152, v98, v99
	v_cvt_pk_f16_f32 v153, v100, v101
	ds_read_b64_tr_b16 v[98:99], v192 offset:30720
	ds_read_b64_tr_b16 v[100:101], v192 offset:31232
	s_waitcnt lgkmcnt(14)
	v_mfma_f32_32x32x16_f16 v[66:81], v[180:183], v[136:139], v[66:81]
	v_add_f32_e32 v126, v104, v126
	v_add_f32_e32 v126, v105, v126
	v_add_f32_e32 v126, v106, v126
	v_add_f32_e32 v126, v107, v126
	v_cvt_pk_f16_f32 v154, v102, v103
	v_cvt_pk_f16_f32 v155, v104, v105
	ds_read_b64_tr_b16 v[102:103], v192 offset:27648
	ds_read_b64_tr_b16 v[104:105], v192 offset:28160
	s_waitcnt lgkmcnt(14)
	v_mfma_f32_32x32x16_f16 v[82:97], v[184:187], v[132:135], v[82:97]
	v_add_f32_e32 v126, v108, v126
	v_add_f32_e32 v126, v109, v126
	v_add_f32_e32 v126, v110, v126
	v_add_f32_e32 v126, v111, v126
	v_cvt_pk_f16_f32 v148, v106, v107
	v_cvt_pk_f16_f32 v149, v108, v109
	ds_read_b64_tr_b16 v[106:107], v192 offset:31744
	ds_read_b64_tr_b16 v[108:109], v192 offset:32256
	v_mfma_f32_32x32x16_f16 v[66:81], v[50:53], v[132:135], v[66:81]
	v_add_f32_e32 v50, v112, v126
	v_add_f32_e32 v50, v113, v50
	v_add_f32_e32 v50, 0, v50
	s_nop 0
	v_cvt_pk_f16_f32 v150, v110, v111
	v_cvt_pk_f16_f32 v151, v112, v113
	s_add_i32 s42, s25, s97
	s_mov_b32 s44, m0
	s_mov_b32 m0, s42
	s_nop 0
	global_load_lds_dwordx4 v214, s[100:101]
	s_mov_b32 m0, s44
	s_add_i32 s42, s43, s83
	s_mov_b32 s44, m0
	s_mov_b32 m0, s42
	s_nop 0
	global_load_lds_dwordx4 v208, vcc
	s_mov_b32 m0, s44
	s_add_u32 s100, s100, 0x2000
	s_addc_u32 s101, s101, 0
	s_add_u32 vcc_lo, vcc_lo, 0x2000
	s_addc_u32 vcc_hi, vcc_hi, 0
	v_add_f32_e32 v50, v0, v50
	s_waitcnt lgkmcnt(14)
	v_mfma_f32_32x32x16_f16 v[18:33], v[160:163], v[188:191], v[18:33]
	v_exp_f32_e32 v82, v82
	v_exp_f32_e32 v83, v83
	v_exp_f32_e32 v84, v84
	v_exp_f32_e32 v85, v85
	s_waitcnt lgkmcnt(12)
	v_mfma_f32_32x32x16_f16 v[34:49], v[160:163], v[62:65], v[34:49]
	v_exp_f32_e32 v86, v86
	v_exp_f32_e32 v87, v87
	v_exp_f32_e32 v88, v88
	v_exp_f32_e32 v89, v89
	v_add_u32_e32 v0, s43, v219
	ds_read_b128 v[192:195], v0
	ds_read_b128 v[188:191], v0 offset:512
	s_waitcnt lgkmcnt(12)
	v_mfma_f32_32x32x16_f16 v[18:33], v[156:159], v[114:117], v[18:33]
	v_exp_f32_e32 v90, v90
	v_exp_f32_e32 v91, v91
	v_exp_f32_e32 v92, v92
	v_exp_f32_e32 v93, v93
	ds_read_b128 v[184:187], v0 offset:2048
	ds_read_b128 v[180:183], v0 offset:2560
	s_waitcnt lgkmcnt(12)
	v_mfma_f32_32x32x16_f16 v[34:49], v[156:159], v[118:121], v[34:49]
	v_exp_f32_e32 v94, v94
	v_exp_f32_e32 v95, v95
	v_exp_f32_e32 v96, v96
	v_exp_f32_e32 v97, v97
	ds_read_b128 v[176:179], v0 offset:4096
	ds_read_b128 v[172:175], v0 offset:4608
	s_waitcnt lgkmcnt(12)
	v_mfma_f32_32x32x16_f16 v[18:33], v[152:155], v[122:125], v[18:33]
	v_exp_f32_e32 v66, v66
	v_exp_f32_e32 v67, v67
	v_exp_f32_e32 v68, v68
	v_exp_f32_e32 v69, v69
	ds_read_b128 v[168:171], v0 offset:6144
	ds_read_b128 v[164:167], v0 offset:6656
	s_waitcnt lgkmcnt(12)
	v_mfma_f32_32x32x16_f16 v[34:49], v[152:155], v[98:101], v[34:49]
	v_exp_f32_e32 v70, v70
	v_exp_f32_e32 v71, v71
	v_exp_f32_e32 v72, v72
	v_exp_f32_e32 v73, v73
	s_waitcnt lgkmcnt(10)
	v_mfma_f32_32x32x16_f16 v[18:33], v[148:151], v[102:105], v[18:33]
	v_exp_f32_e32 v74, v74
	v_exp_f32_e32 v75, v75
	v_exp_f32_e32 v76, v76
	v_exp_f32_e32 v77, v77
	s_waitcnt lgkmcnt(8)
	v_mfma_f32_32x32x16_f16 v[34:49], v[148:151], v[106:109], v[34:49]
	v_exp_f32_e32 v78, v78
	v_exp_f32_e32 v79, v79
	v_exp_f32_e32 v80, v80
	v_exp_f32_e32 v81, v81
	s_add_i32 s45, s43, 0x2000
	s_waitcnt vmcnt(2) lgkmcnt(8)
	s_barrier
	s_cmpk_lg_i32 s43, 0x4000
	s_mov_b32 s44, s25
	s_cselect_b32 s25, s45, 0
	s_add_i32 s24, s24, 2
	v_lshl_add_u64 v[54:55], v[54:55], 0, s[62:63]
	v_lshl_add_u64 v[56:57], v[56:57], 0, s[62:63]
	s_mov_b32 s42, s43
	s_cmp_lt_u32 s24, 29
	s_cbranch_scc1 .LBB0_77
	s_nop 0
	s_mov_b64 s[36:37], 0x10c84000
	s_mov_b64 s[60:61], 0x10388000
	s_mov_b32 s45, 31
	s_branch .LBB0_80
